# v11: attn LSE/O hoist, scan pass2 balance, GEMM K-loop peel (no acc zeroing), EpiRes loads upfront, hand-written scale epilogue with per-pm cached rstd
# speedup vs baseline: 1.0173x; 1.0106x over previous
; #define PG8_STAGE(bufoff, gbase, voff) do { _Pragma("unroll") for (int _i = 0; _i < 2; ++_i) \
;         __builtin_amdgcn_global_load_lds((const unsigned*)((const char*)(gbase) + (voff)[_i]), (PG8_LAS unsigned*)(lds + (bufoff) + ldsw + _i * 8192), 16, 0, 0); } while (0)
; #define PG8_WAIT_V(n) asm volatile("s_waitcnt vmcnt(" #n ")" ::: "memory")
; #define PG8_BAR __builtin_amdgcn_s_barrier()
; template <class Epi, class Sched, bool ALIGN_EPI = false, bool SP2 = false>
; __device__ __forceinline__ void gemm_phase(PG8_LAS unsigned char* lds, const Gemm g, const Sched& S, const Epi& E) {
;     ...
;     const char* cA = (const char*)g.A + (size_t)cur.pm * tstep; const char* cB = (const char*)g.Bt + (size_t)cur.pn * tstep;
;     S.a_ready(cur);
;     if constexpr (SP2) {
;         PG8_STAGE(PG8_SB(0, 0), cB, voffB); PG8_STAGE(PG8_SB(0, 1), cB + hstep, voffB); PG8_STAGE(PG8_SA(0, 0), cA, voffA); PG8_STAGE(PG8_SA(0, 1), cA + hstep, voffA);
;         if (wr == 1) PG8_BAR;
;         PG8_WAIT_V(2); PG8_BAR;
;         PG8_STAGE(PG8_SB(1, 0), cB + kstep, voffB); PG8_STAGE(PG8_SA(1, 0), cA + kstep, voffA); PG8_STAGE(PG8_SB(1, 1), cB + hstep + kstep, voffB);
;         PG8_WAIT_V(6); PG8_BAR;
;     } else {
;         PG8_STAGE(PG8_SB(0, 0), cB, voffB); PG8_STAGE(PG8_SA(0, 0), cA, voffA); PG8_STAGE(PG8_SB(0, 1), cB + hstep, voffB); PG8_STAGE(PG8_SA(0, 1), cA + hstep, voffA);
;         if (wr == 1) PG8_BAR;
;         PG8_WAIT_V(4); PG8_BAR;
;         PG8_STAGE(PG8_SB(1, 0), cB + kstep, voffB); PG8_STAGE(PG8_SA(1, 0), cA + kstep, voffA); PG8_STAGE(PG8_SB(1, 1), cB + hstep + kstep, voffB);
;         PG8_WAIT_V(6); PG8_BAR;
.LBB0_217:
	s_mov_b32 s100, -1
	s_and_b64 s[4:5], s[24:25], s[4:5]
	v_readlane_b32 s40, v251, 0
	s_and_b64 s[10:11], s[4:5], exec
	v_readlane_b32 s41, v251, 1
	s_cselect_b32 s57, s41, s83
	s_cselect_b32 s56, s40, s82
	s_add_u32 s10, s34, 0x14000000
	s_addc_u32 s11, s35, 0
	s_and_b64 s[4:5], s[4:5], exec
	v_readlane_b32 s4, v251, 29
	s_cselect_b32 s68, s4, s11
	v_readlane_b32 s4, v251, 28
	s_cselect_b32 s69, s4, s10
	s_brev_b32 s4, 56
	s_cselect_b32 s4, s4, 0x18000000
	s_add_u32 s82, s34, s4
	s_addc_u32 s83, s35, 0
	s_add_i32 m0, s36, 0x18000
	v_lshl_add_u64 v[10:11], v[10:11], 0, s[98:99]
	s_waitcnt vmcnt(2)
	s_barrier
	global_load_lds_dwordx4 v[10:11], off
	v_lshl_add_u64 v[6:7], v[6:7], 0, s[98:99]
	s_add_i32 m0, s36, 0x1a000
	s_add_i32 s86, s36, 0x8000
	global_load_lds_dwordx4 v[6:7], off
	v_lshl_add_u64 v[6:7], v[8:9], 0, s[98:99]
	s_mov_b32 m0, s86
	s_add_i32 s87, s36, 0xa000
	global_load_lds_dwordx4 v[6:7], off
	v_lshl_add_u64 v[6:7], v[12:13], 0, s[98:99]
	s_mov_b32 m0, s87
	v_lshl_add_u64 v[4:5], v[4:5], 0, s[98:99]
	global_load_lds_dwordx4 v[6:7], off
	s_add_i32 m0, s36, 0x1c000
	v_lshl_add_u64 v[2:3], v[2:3], 0, s[98:99]
	global_load_lds_dwordx4 v[4:5], off
	s_add_i32 m0, s36, 0x1e000
	v_and_b32_e32 v4, 15, v15
	global_load_lds_dwordx4 v[2:3], off
	v_bfe_u32 v3, v15, 4, 2
	v_lshlrev_b32_e32 v2, 4, v3
	v_lshlrev_b32_e32 v6, 2, v15
	s_and_b32 s89, s8, 3
	v_lshl_or_b32 v199, s9, 6, v4
	v_lshl_or_b32 v4, v4, 6, v2
	s_lshl_b32 s4, s9, 13
	v_and_b32_e32 v6, 32, v6
	v_bitop3_b32 v7, v4, s4, v6 bitop3:0xde
	s_lshl_b32 s4, s89, 12
	v_bitop3_b32 v200, v4, s4, v6 bitop3:0xde
	v_rcp_iflag_f32_e32 v4, v14
	v_lshlrev_b32_e32 v5, 3, v3
	v_cmp_eq_u32_e64 s[38:39], 0, v3
	v_mov_b32_e32 v3, v1
	s_lshr_b32 s90, s6, 6
	v_lshl_add_u64 v[166:167], s[34:35], 0, v[2:3]
	v_mul_f32_e32 v2, 0x4f7ffffe, v4
	s_add_i32 s91, s90, -2
	v_cvt_u32_f32_e32 v2, v2
	s_cmpk_lt_u32 s7, 0x100
	s_cselect_b64 s[58:59], -1, 0
	s_lshr_b32 s10, s2, 4
	s_and_b64 s[4:5], s[24:25], exec
	v_readfirstlane_b32 s4, v2
	v_add_u32_e32 v2, v21, v19
	s_cselect_b32 s11, 0x400, s2
	s_sub_i32 s2, 0, s20
	v_add_lshl_u32 v2, v2, v20, 1
	s_waitcnt vmcnt(6)
	s_mul_i32 s2, s2, s4
	v_lshl_add_u64 v[168:169], s[50:51], 0, v[2:3]
	v_add_u32_e32 v2, v18, v16
	s_mul_hi_u32 s2, s4, s2
	v_add_lshl_u32 v2, v2, v17, 1
	s_mov_b32 s88, 0
	s_mov_b32 s49, s95
	v_lshl_or_b32 v201, s89, 5, v5
	s_add_i32 s14, s4, s2
	v_lshl_add_u64 v[170:171], s[50:51], 0, v[2:3]
	v_add_u32_e32 v202, 0, v7
	v_readlane_b32 s42, v251, 2
	v_readlane_b32 s43, v251, 3
	s_barrier
	s_branch .LBB0_220

;     __device__ __forceinline__ void operator()(const f32x4 (&acc)[2][2][4][2], const Unit& u, int wr, int wc, int fr, int fq) const {
;         if (mode == 0) { EpiScaleBf16<0> e{O, ldc, ssq_in, O1, O2, split}; e(acc, u, wr, wc, fr, fq); }
;         else if (mode == 1) { EpiScaleBf16<1> e{O, ldc, ssq_in, O, O, 0}; e(acc, u, wr, wc, fr, fq); }
;         else { EpiRes e{xb, ssq_out}; e(acc, u, wr, wc, fr, fq); }
.LBB0_251:
	s_and_b64 vcc, exec, s[4:5]
	s_cbranch_vccz .LBB0_253
	s_branch .LBB0_254

; #define PG8_GAS __attribute__((address_space(1)))
; __device__ __forceinline__ unsigned cvt_pk_bf16(float lo, float hi) { unsigned r; asm volatile("v_cvt_pk_bf16_f32 %0, %1, %2" : "=v"(r) : "v"(lo), "v"(hi)); return r; }
;     __device__ __forceinline__ void operator()(const f32x4 (&acc)[2][2][4][2], const Unit& u, int wr, int wc, int fr, int fq) const {
;         const int row0 = u.pm * BM + wr * 64 + fr; int colt = u.pn * BM; bf16_t* Ob = O;
;         if (split) { const int t = colt >> 10; colt &= 1023; Ob = t == 0 ? O : (t == 1 ? O1 : O2); }
;         const int col0 = colt + wc * 32 + 8 * fq;
;         f32x4 pv[2][4];
; #pragma unroll
;         for (int ai = 0; ai < 2; ++ai)
; #pragma unroll
;             for (int m = 0; m < 4; ++m) pv[ai][m] = *(const PG8_GAS f32x4*)(ssq + (size_t)(row0 + ai * HALF + m * 16) * 16 + 4 * fq);
;         float rsv[2][4];
; #pragma unroll
;         for (int ai = 0; ai < 2; ++ai)
; #pragma unroll
;             for (int m = 0; m < 4; ++m) { float s = (pv[ai][m][0] + pv[ai][m][1]) + (pv[ai][m][2] + pv[ai][m][3]); s += __shfl_xor(s, 16); s += __shfl_xor(s, 32);
;                 rsv[ai][m] = __builtin_amdgcn_rsqf(s * (1.0f / 1024.0f) + NORM_EPS); }
;     ...
;         for (int ai = 0; ai < 2; ++ai)
; #pragma unroll
;             for (int m = 0; m < 4; ++m) {
;                 const int row = row0 + ai * HALF + m * 16; const float rs = rsv[ai][m];
;                 bf16_t* rowp = Ob + (size_t)row * ldc + col0;
; #pragma unroll
;                 for (int bj = 0; bj < 2; ++bj) { f32x4 v0 = acc[ai][bj][m][0] * rs, v1 = acc[ai][bj][m][1] * rs;
;                     if (ACT == 1) {
; #pragma unroll
;                         for (int e = 0; e < 4; ++e) { const float a = fmaxf(v0[e], 0.f), b = fmaxf(v1[e], 0.f); v0[e] = a * a; v1[e] = b * b; } }
;                     u32x4 w; w.x = cvt_pk_bf16(v0[0], v0[1]); w.y = cvt_pk_bf16(v0[2], v0[3]); w.z = cvt_pk_bf16(v1[0], v1[1]); w.w = cvt_pk_bf16(v1[2], v1[3]);
;                     *(PG8_GAS u32x4*)(rowp + bj * HALF) = w; } }
.LBB0_254:
	s_cmp_eq_u32 s26, s100
	s_cbranch_scc1 .Lmy_rstd_ok
	v_lshl_add_u32 v130, s26, 8, v199
	v_mov_b32_e32 v131, 0
	v_lshlrev_b64 v[132:133], 6, v[130:131]
	v_lshl_add_u64 v[132:133], v[166:167], 0, v[132:133]
	s_mov_b64 s[6:7], 0x2000
	global_load_dwordx4 v[204:207], v[132:133], off
	global_load_dwordx4 v[208:211], v[132:133], off offset:1024
	global_load_dwordx4 v[212:215], v[132:133], off offset:2048
	global_load_dwordx4 v[216:219], v[132:133], off offset:3072
	v_lshl_add_u64 v[132:133], v[132:133], 0, s[6:7]
	global_load_dwordx4 v[220:223], v[132:133], off
	global_load_dwordx4 v[224:227], v[132:133], off offset:1024
	global_load_dwordx4 v[228:231], v[132:133], off offset:2048
	global_load_dwordx4 v[232:235], v[132:133], off offset:3072
	v_xor_b32_e32 v134, 16, v190
	v_xor_b32_e32 v135, 32, v190
	v_lshlrev_b32_e32 v134, 2, v134
	v_lshlrev_b32_e32 v135, 2, v135
	s_waitcnt vmcnt(0)
	v_add_f32_e32 v136, v204, v205
	v_add_f32_e32 v144, v206, v207
	v_add_f32_e32 v137, v208, v209
	v_add_f32_e32 v145, v210, v211
	v_add_f32_e32 v138, v212, v213
	v_add_f32_e32 v146, v214, v215
	v_add_f32_e32 v139, v216, v217
	v_add_f32_e32 v147, v218, v219
	v_add_f32_e32 v140, v220, v221
	v_add_f32_e32 v148, v222, v223
	v_add_f32_e32 v141, v224, v225
	v_add_f32_e32 v149, v226, v227
	v_add_f32_e32 v142, v228, v229
	v_add_f32_e32 v150, v230, v231
	v_add_f32_e32 v143, v232, v233
	v_add_f32_e32 v151, v234, v235
	v_add_f32_e32 v136, v136, v144
	v_add_f32_e32 v137, v137, v145
	v_add_f32_e32 v138, v138, v146
	v_add_f32_e32 v139, v139, v147
	v_add_f32_e32 v140, v140, v148
	v_add_f32_e32 v141, v141, v149
	v_add_f32_e32 v142, v142, v150
	v_add_f32_e32 v143, v143, v151
	ds_bpermute_b32 v144, v134, v136
	ds_bpermute_b32 v145, v134, v137
	ds_bpermute_b32 v146, v134, v138
	ds_bpermute_b32 v147, v134, v139
	ds_bpermute_b32 v148, v134, v140
	ds_bpermute_b32 v149, v134, v141
	ds_bpermute_b32 v150, v134, v142
	ds_bpermute_b32 v151, v134, v143
	s_waitcnt lgkmcnt(0)
	v_add_f32_e32 v136, v136, v144
	v_add_f32_e32 v137, v137, v145
	v_add_f32_e32 v138, v138, v146
	v_add_f32_e32 v139, v139, v147
	v_add_f32_e32 v140, v140, v148
	v_add_f32_e32 v141, v141, v149
	v_add_f32_e32 v142, v142, v150
	v_add_f32_e32 v143, v143, v151
	ds_bpermute_b32 v144, v135, v136
	ds_bpermute_b32 v145, v135, v137
	ds_bpermute_b32 v146, v135, v138
	ds_bpermute_b32 v147, v135, v139
	ds_bpermute_b32 v148, v135, v140
	ds_bpermute_b32 v149, v135, v141
	ds_bpermute_b32 v150, v135, v142
	ds_bpermute_b32 v151, v135, v143
	s_waitcnt lgkmcnt(0)
	v_add_f32_e32 v136, v136, v144
	v_add_f32_e32 v137, v137, v145
	v_add_f32_e32 v138, v138, v146
	v_add_f32_e32 v139, v139, v147
	v_add_f32_e32 v140, v140, v148
	v_add_f32_e32 v141, v141, v149
	v_add_f32_e32 v142, v142, v150
	v_add_f32_e32 v143, v143, v151
	v_fmamk_f32 v136, v136, 0x3a800000, v192
	v_fmamk_f32 v137, v137, 0x3a800000, v192
	v_fmamk_f32 v138, v138, 0x3a800000, v192
	v_fmamk_f32 v139, v139, 0x3a800000, v192
	v_fmamk_f32 v140, v140, 0x3a800000, v192
	v_fmamk_f32 v141, v141, 0x3a800000, v192
	v_fmamk_f32 v142, v142, 0x3a800000, v192
	v_fmamk_f32 v143, v143, 0x3a800000, v192
	v_rsq_f32_e32 v236, v136
	v_rsq_f32_e32 v238, v137
	v_rsq_f32_e32 v240, v138
	v_rsq_f32_e32 v242, v139
	v_rsq_f32_e32 v244, v140
	v_rsq_f32_e32 v246, v141
	v_rsq_f32_e32 v248, v142
	v_rsq_f32_e32 v252, v143
	s_mov_b32 s100, s26
.Lmy_rstd_ok:
	s_lshl_b32 s2, s27, 8
	s_and_b32 s6, s2, 0x300
	s_cmp_gt_u32 s27, 3
	s_cselect_b64 s[4:5], -1, 0
	s_cmp_lt_u32 s27, 8
	s_cselect_b32 s7, s69, s82
	s_cselect_b32 s9, s68, s83
	s_and_b64 s[4:5], s[24:25], s[4:5]
	s_and_b64 s[4:5], s[4:5], exec
	s_cselect_b32 s9, s9, s57
	s_cselect_b32 s7, s7, s56
	s_and_b64 s[4:5], s[24:25], exec
	s_cselect_b32 s2, s6, s2
	v_or_b32_e32 v140, s2, v201
	v_mov_b32_e32 v141, 0
	v_mov_b32_e32 v142, s7
	v_mov_b32_e32 v143, s9
	v_lshl_add_u64 v[140:141], v[140:141], 1, v[142:143]
	v_lshl_add_u32 v130, s26, 8, v199
	s_lshl_b32 s6, s11, 1
	v_mul_lo_u32 v142, v130, s6
	v_mov_b32_e32 v143, 0
	v_lshl_add_u64 v[140:141], v[140:141], 0, v[142:143]
	s_lshl_b32 s6, s11, 5
	s_mov_b32 s7, 0
	s_mul_i32 s4, s11, 0xa0
	s_mov_b32 s5, 0
	s_cmp_eq_u32 s15, 1
	s_cbranch_scc1 .Lmy_epi_relu2
	v_pk_mul_f32 v[144:145], v[126:127], v[236:237] op_sel_hi:[1,0]
	v_pk_mul_f32 v[146:147], v[128:129], v[236:237] op_sel_hi:[1,0]
	v_pk_mul_f32 v[148:149], v[122:123], v[236:237] op_sel_hi:[1,0]
	v_pk_mul_f32 v[150:151], v[124:125], v[236:237] op_sel_hi:[1,0]
	v_cvt_pk_bf16_f32 v152, v144, v145
	v_cvt_pk_bf16_f32 v153, v146, v147
	v_cvt_pk_bf16_f32 v154, v148, v149
	v_cvt_pk_bf16_f32 v155, v150, v151
	global_store_dwordx4 v[140:141], v[152:155], off
	v_pk_mul_f32 v[172:173], v[118:119], v[236:237] op_sel_hi:[1,0]
	v_pk_mul_f32 v[174:175], v[120:121], v[236:237] op_sel_hi:[1,0]
	v_pk_mul_f32 v[176:177], v[114:115], v[236:237] op_sel_hi:[1,0]
	v_pk_mul_f32 v[178:179], v[116:117], v[236:237] op_sel_hi:[1,0]
	v_cvt_pk_bf16_f32 v180, v172, v173
	v_cvt_pk_bf16_f32 v181, v174, v175
	v_cvt_pk_bf16_f32 v182, v176, v177
	v_cvt_pk_bf16_f32 v183, v178, v179
	global_store_dwordx4 v[140:141], v[180:183], off offset:256
	v_lshl_add_u64 v[140:141], v[140:141], 0, s[6:7]
	v_pk_mul_f32 v[144:145], v[110:111], v[238:239] op_sel_hi:[1,0]
	v_pk_mul_f32 v[146:147], v[112:113], v[238:239] op_sel_hi:[1,0]
	v_pk_mul_f32 v[148:149], v[106:107], v[238:239] op_sel_hi:[1,0]
	v_pk_mul_f32 v[150:151], v[108:109], v[238:239] op_sel_hi:[1,0]
	v_cvt_pk_bf16_f32 v152, v144, v145
	v_cvt_pk_bf16_f32 v153, v146, v147
	v_cvt_pk_bf16_f32 v154, v148, v149
	v_cvt_pk_bf16_f32 v155, v150, v151
	global_store_dwordx4 v[140:141], v[152:155], off
	v_pk_mul_f32 v[172:173], v[102:103], v[238:239] op_sel_hi:[1,0]
; #define PG8_GAS __attribute__((address_space(1)))
; __device__ __forceinline__ unsigned cvt_pk_bf16(float lo, float hi) { unsigned r; asm volatile("v_cvt_pk_bf16_f32 %0, %1, %2" : "=v"(r) : "v"(lo), "v"(hi)); return r; }
;     __device__ __forceinline__ void operator()(const f32x4 (&acc)[2][2][4][2], const Unit& u, int wr, int wc, int fr, int fq) const {
;     ...
;         for (int ai = 0; ai < 2; ++ai)
; #pragma unroll
;             for (int m = 0; m < 4; ++m) {
;                 const int row = row0 + ai * HALF + m * 16; const float rs = rsv[ai][m];
;                 bf16_t* rowp = Ob + (size_t)row * ldc + col0;
; #pragma unroll
;                 for (int bj = 0; bj < 2; ++bj) { f32x4 v0 = acc[ai][bj][m][0] * rs, v1 = acc[ai][bj][m][1] * rs;
;                     if (ACT == 1) {
; #pragma unroll
;                         for (int e = 0; e < 4; ++e) { const float a = fmaxf(v0[e], 0.f), b = fmaxf(v1[e], 0.f); v0[e] = a * a; v1[e] = b * b; } }
;                     u32x4 w; w.x = cvt_pk_bf16(v0[0], v0[1]); w.y = cvt_pk_bf16(v0[2], v0[3]); w.z = cvt_pk_bf16(v1[0], v1[1]); w.w = cvt_pk_bf16(v1[2], v1[3]);
;                     *(PG8_GAS u32x4*)(rowp + bj * HALF) = w; } }
	v_pk_mul_f32 v[174:175], v[104:105], v[238:239] op_sel_hi:[1,0]
	v_pk_mul_f32 v[176:177], v[98:99], v[238:239] op_sel_hi:[1,0]
	v_pk_mul_f32 v[178:179], v[100:101], v[238:239] op_sel_hi:[1,0]
	v_cvt_pk_bf16_f32 v180, v172, v173
	v_cvt_pk_bf16_f32 v181, v174, v175
	v_cvt_pk_bf16_f32 v182, v176, v177
	v_cvt_pk_bf16_f32 v183, v178, v179
	global_store_dwordx4 v[140:141], v[180:183], off offset:256
	v_lshl_add_u64 v[140:141], v[140:141], 0, s[6:7]
	v_pk_mul_f32 v[144:145], v[94:95], v[240:241] op_sel_hi:[1,0]
	v_pk_mul_f32 v[146:147], v[96:97], v[240:241] op_sel_hi:[1,0]
	v_pk_mul_f32 v[148:149], v[90:91], v[240:241] op_sel_hi:[1,0]
	v_pk_mul_f32 v[150:151], v[92:93], v[240:241] op_sel_hi:[1,0]
	v_cvt_pk_bf16_f32 v152, v144, v145
	v_cvt_pk_bf16_f32 v153, v146, v147
	v_cvt_pk_bf16_f32 v154, v148, v149
	v_cvt_pk_bf16_f32 v155, v150, v151
	global_store_dwordx4 v[140:141], v[152:155], off
	v_pk_mul_f32 v[172:173], v[86:87], v[240:241] op_sel_hi:[1,0]
	v_pk_mul_f32 v[174:175], v[88:89], v[240:241] op_sel_hi:[1,0]
	v_pk_mul_f32 v[176:177], v[82:83], v[240:241] op_sel_hi:[1,0]
	v_pk_mul_f32 v[178:179], v[84:85], v[240:241] op_sel_hi:[1,0]
	v_cvt_pk_bf16_f32 v180, v172, v173
	v_cvt_pk_bf16_f32 v181, v174, v175
	v_cvt_pk_bf16_f32 v182, v176, v177
	v_cvt_pk_bf16_f32 v183, v178, v179
	global_store_dwordx4 v[140:141], v[180:183], off offset:256
	v_lshl_add_u64 v[140:141], v[140:141], 0, s[6:7]
	v_pk_mul_f32 v[144:145], v[78:79], v[242:243] op_sel_hi:[1,0]
	v_pk_mul_f32 v[146:147], v[80:81], v[242:243] op_sel_hi:[1,0]
	v_pk_mul_f32 v[148:149], v[74:75], v[242:243] op_sel_hi:[1,0]
	v_pk_mul_f32 v[150:151], v[76:77], v[242:243] op_sel_hi:[1,0]
	v_cvt_pk_bf16_f32 v152, v144, v145
	v_cvt_pk_bf16_f32 v153, v146, v147
	v_cvt_pk_bf16_f32 v154, v148, v149
	v_cvt_pk_bf16_f32 v155, v150, v151
	global_store_dwordx4 v[140:141], v[152:155], off
	v_pk_mul_f32 v[172:173], v[70:71], v[242:243] op_sel_hi:[1,0]
	v_pk_mul_f32 v[174:175], v[72:73], v[242:243] op_sel_hi:[1,0]
	v_pk_mul_f32 v[176:177], v[66:67], v[242:243] op_sel_hi:[1,0]
	v_pk_mul_f32 v[178:179], v[68:69], v[242:243] op_sel_hi:[1,0]
	v_cvt_pk_bf16_f32 v180, v172, v173
	v_cvt_pk_bf16_f32 v181, v174, v175
	v_cvt_pk_bf16_f32 v182, v176, v177
	v_cvt_pk_bf16_f32 v183, v178, v179
	global_store_dwordx4 v[140:141], v[180:183], off offset:256
	v_lshl_add_u64 v[140:141], v[140:141], 0, s[4:5]
	v_pk_mul_f32 v[144:145], v[62:63], v[244:245] op_sel_hi:[1,0]
	v_pk_mul_f32 v[146:147], v[64:65], v[244:245] op_sel_hi:[1,0]
	v_pk_mul_f32 v[148:149], v[58:59], v[244:245] op_sel_hi:[1,0]
	v_pk_mul_f32 v[150:151], v[60:61], v[244:245] op_sel_hi:[1,0]
	v_cvt_pk_bf16_f32 v152, v144, v145
	v_cvt_pk_bf16_f32 v153, v146, v147
	v_cvt_pk_bf16_f32 v154, v148, v149
	v_cvt_pk_bf16_f32 v155, v150, v151
	global_store_dwordx4 v[140:141], v[152:155], off
	v_pk_mul_f32 v[172:173], v[54:55], v[244:245] op_sel_hi:[1,0]
	v_pk_mul_f32 v[174:175], v[56:57], v[244:245] op_sel_hi:[1,0]
	v_pk_mul_f32 v[176:177], v[50:51], v[244:245] op_sel_hi:[1,0]
	v_pk_mul_f32 v[178:179], v[52:53], v[244:245] op_sel_hi:[1,0]
	v_cvt_pk_bf16_f32 v180, v172, v173
	v_cvt_pk_bf16_f32 v181, v174, v175
	v_cvt_pk_bf16_f32 v182, v176, v177
	v_cvt_pk_bf16_f32 v183, v178, v179
	global_store_dwordx4 v[140:141], v[180:183], off offset:256
	v_lshl_add_u64 v[140:141], v[140:141], 0, s[6:7]
	v_pk_mul_f32 v[144:145], v[46:47], v[246:247] op_sel_hi:[1,0]
	v_pk_mul_f32 v[146:147], v[48:49], v[246:247] op_sel_hi:[1,0]
	v_pk_mul_f32 v[148:149], v[42:43], v[246:247] op_sel_hi:[1,0]
	v_pk_mul_f32 v[150:151], v[44:45], v[246:247] op_sel_hi:[1,0]
	v_cvt_pk_bf16_f32 v152, v144, v145
	v_cvt_pk_bf16_f32 v153, v146, v147
	v_cvt_pk_bf16_f32 v154, v148, v149
	v_cvt_pk_bf16_f32 v155, v150, v151
	global_store_dwordx4 v[140:141], v[152:155], off
	v_pk_mul_f32 v[172:173], v[38:39], v[246:247] op_sel_hi:[1,0]
	v_pk_mul_f32 v[174:175], v[40:41], v[246:247] op_sel_hi:[1,0]
	v_pk_mul_f32 v[176:177], v[34:35], v[246:247] op_sel_hi:[1,0]
	v_pk_mul_f32 v[178:179], v[36:37], v[246:247] op_sel_hi:[1,0]
	v_cvt_pk_bf16_f32 v180, v172, v173
	v_cvt_pk_bf16_f32 v181, v174, v175
	v_cvt_pk_bf16_f32 v182, v176, v177
	v_cvt_pk_bf16_f32 v183, v178, v179
	global_store_dwordx4 v[140:141], v[180:183], off offset:256
	v_lshl_add_u64 v[140:141], v[140:141], 0, s[6:7]
	v_pk_mul_f32 v[144:145], v[30:31], v[248:249] op_sel_hi:[1,0]
	v_pk_mul_f32 v[146:147], v[32:33], v[248:249] op_sel_hi:[1,0]
	v_pk_mul_f32 v[148:149], v[26:27], v[248:249] op_sel_hi:[1,0]
	v_pk_mul_f32 v[150:151], v[28:29], v[248:249] op_sel_hi:[1,0]
	v_cvt_pk_bf16_f32 v152, v144, v145
	v_cvt_pk_bf16_f32 v153, v146, v147
	v_cvt_pk_bf16_f32 v154, v148, v149
	v_cvt_pk_bf16_f32 v155, v150, v151
	global_store_dwordx4 v[140:141], v[152:155], off
	v_pk_mul_f32 v[172:173], v[22:23], v[248:249] op_sel_hi:[1,0]
	v_pk_mul_f32 v[174:175], v[24:25], v[248:249] op_sel_hi:[1,0]
	v_pk_mul_f32 v[176:177], v[18:19], v[248:249] op_sel_hi:[1,0]
	v_pk_mul_f32 v[178:179], v[20:21], v[248:249] op_sel_hi:[1,0]
	v_cvt_pk_bf16_f32 v180, v172, v173
	v_cvt_pk_bf16_f32 v181, v174, v175
	v_cvt_pk_bf16_f32 v182, v176, v177
	v_cvt_pk_bf16_f32 v183, v178, v179
	global_store_dwordx4 v[140:141], v[180:183], off offset:256
	v_lshl_add_u64 v[140:141], v[140:141], 0, s[6:7]
	v_pk_mul_f32 v[144:145], v[14:15], v[252:253] op_sel_hi:[1,0]
	v_pk_mul_f32 v[146:147], v[16:17], v[252:253] op_sel_hi:[1,0]
	v_pk_mul_f32 v[148:149], v[10:11], v[252:253] op_sel_hi:[1,0]
	v_pk_mul_f32 v[150:151], v[12:13], v[252:253] op_sel_hi:[1,0]
	v_cvt_pk_bf16_f32 v152, v144, v145
	v_cvt_pk_bf16_f32 v153, v146, v147
	v_cvt_pk_bf16_f32 v154, v148, v149
	v_cvt_pk_bf16_f32 v155, v150, v151
	global_store_dwordx4 v[140:141], v[152:155], off
	v_pk_mul_f32 v[172:173], v[6:7], v[252:253] op_sel_hi:[1,0]
	v_pk_mul_f32 v[174:175], v[8:9], v[252:253] op_sel_hi:[1,0]
	v_pk_mul_f32 v[176:177], v[2:3], v[252:253] op_sel_hi:[1,0]
	v_pk_mul_f32 v[178:179], v[4:5], v[252:253] op_sel_hi:[1,0]
	v_cvt_pk_bf16_f32 v180, v172, v173
	v_cvt_pk_bf16_f32 v181, v174, v175
	v_cvt_pk_bf16_f32 v182, v176, v177
	v_cvt_pk_bf16_f32 v183, v178, v179
	global_store_dwordx4 v[140:141], v[180:183], off offset:256
	s_branch .Lmy_epi_done
; #define PG8_GAS __attribute__((address_space(1)))
; __device__ __forceinline__ unsigned cvt_pk_bf16(float lo, float hi) { unsigned r; asm volatile("v_cvt_pk_bf16_f32 %0, %1, %2" : "=v"(r) : "v"(lo), "v"(hi)); return r; }
;     __device__ __forceinline__ void operator()(const f32x4 (&acc)[2][2][4][2], const Unit& u, int wr, int wc, int fr, int fq) const {
;     ...
;                 for (int bj = 0; bj < 2; ++bj) { f32x4 v0 = acc[ai][bj][m][0] * rs, v1 = acc[ai][bj][m][1] * rs;
;                     if (ACT == 1) {
; #pragma unroll
;                         for (int e = 0; e < 4; ++e) { const float a = fmaxf(v0[e], 0.f), b = fmaxf(v1[e], 0.f); v0[e] = a * a; v1[e] = b * b; } }
;                     u32x4 w; w.x = cvt_pk_bf16(v0[0], v0[1]); w.y = cvt_pk_bf16(v0[2], v0[3]); w.z = cvt_pk_bf16(v1[0], v1[1]); w.w = cvt_pk_bf16(v1[2], v1[3]);
;                     *(PG8_GAS u32x4*)(rowp + bj * HALF) = w; } }
.Lmy_epi_relu2:
	v_pk_mul_f32 v[144:145], v[126:127], v[236:237] op_sel_hi:[1,0]
	v_pk_mul_f32 v[146:147], v[128:129], v[236:237] op_sel_hi:[1,0]
	v_pk_mul_f32 v[148:149], v[122:123], v[236:237] op_sel_hi:[1,0]
	v_pk_mul_f32 v[150:151], v[124:125], v[236:237] op_sel_hi:[1,0]
	v_max_f32_e32 v144, 0, v144
	v_max_f32_e32 v145, 0, v145
	v_max_f32_e32 v146, 0, v146
	v_max_f32_e32 v147, 0, v147
	v_max_f32_e32 v148, 0, v148
	v_max_f32_e32 v149, 0, v149
	v_max_f32_e32 v150, 0, v150
	v_max_f32_e32 v151, 0, v151
	v_pk_mul_f32 v[144:145], v[144:145], v[144:145]
	v_pk_mul_f32 v[146:147], v[146:147], v[146:147]
	v_pk_mul_f32 v[148:149], v[148:149], v[148:149]
	v_pk_mul_f32 v[150:151], v[150:151], v[150:151]
	v_cvt_pk_bf16_f32 v152, v144, v145
	v_cvt_pk_bf16_f32 v153, v146, v147
	v_cvt_pk_bf16_f32 v154, v148, v149
	v_cvt_pk_bf16_f32 v155, v150, v151
	global_store_dwordx4 v[140:141], v[152:155], off
	v_pk_mul_f32 v[172:173], v[118:119], v[236:237] op_sel_hi:[1,0]
	v_pk_mul_f32 v[174:175], v[120:121], v[236:237] op_sel_hi:[1,0]
	v_pk_mul_f32 v[176:177], v[114:115], v[236:237] op_sel_hi:[1,0]
	v_pk_mul_f32 v[178:179], v[116:117], v[236:237] op_sel_hi:[1,0]
	v_max_f32_e32 v172, 0, v172
	v_max_f32_e32 v173, 0, v173
	v_max_f32_e32 v174, 0, v174
	v_max_f32_e32 v175, 0, v175
	v_max_f32_e32 v176, 0, v176
	v_max_f32_e32 v177, 0, v177
	v_max_f32_e32 v178, 0, v178
	v_max_f32_e32 v179, 0, v179
	v_pk_mul_f32 v[172:173], v[172:173], v[172:173]
	v_pk_mul_f32 v[174:175], v[174:175], v[174:175]
	v_pk_mul_f32 v[176:177], v[176:177], v[176:177]
	v_pk_mul_f32 v[178:179], v[178:179], v[178:179]
	v_cvt_pk_bf16_f32 v180, v172, v173
	v_cvt_pk_bf16_f32 v181, v174, v175
	v_cvt_pk_bf16_f32 v182, v176, v177
	v_cvt_pk_bf16_f32 v183, v178, v179
	global_store_dwordx4 v[140:141], v[180:183], off offset:256
	v_lshl_add_u64 v[140:141], v[140:141], 0, s[6:7]
	v_pk_mul_f32 v[144:145], v[110:111], v[238:239] op_sel_hi:[1,0]
	v_pk_mul_f32 v[146:147], v[112:113], v[238:239] op_sel_hi:[1,0]
	v_pk_mul_f32 v[148:149], v[106:107], v[238:239] op_sel_hi:[1,0]
	v_pk_mul_f32 v[150:151], v[108:109], v[238:239] op_sel_hi:[1,0]
	v_max_f32_e32 v144, 0, v144
	v_max_f32_e32 v145, 0, v145
	v_max_f32_e32 v146, 0, v146
	v_max_f32_e32 v147, 0, v147
	v_max_f32_e32 v148, 0, v148
	v_max_f32_e32 v149, 0, v149
	v_max_f32_e32 v150, 0, v150
	v_max_f32_e32 v151, 0, v151
	v_pk_mul_f32 v[144:145], v[144:145], v[144:145]
	v_pk_mul_f32 v[146:147], v[146:147], v[146:147]
	v_pk_mul_f32 v[148:149], v[148:149], v[148:149]
	v_pk_mul_f32 v[150:151], v[150:151], v[150:151]
	v_cvt_pk_bf16_f32 v152, v144, v145
	v_cvt_pk_bf16_f32 v153, v146, v147
	v_cvt_pk_bf16_f32 v154, v148, v149
	v_cvt_pk_bf16_f32 v155, v150, v151
	global_store_dwordx4 v[140:141], v[152:155], off
	v_pk_mul_f32 v[172:173], v[102:103], v[238:239] op_sel_hi:[1,0]
	v_pk_mul_f32 v[174:175], v[104:105], v[238:239] op_sel_hi:[1,0]
	v_pk_mul_f32 v[176:177], v[98:99], v[238:239] op_sel_hi:[1,0]
	v_pk_mul_f32 v[178:179], v[100:101], v[238:239] op_sel_hi:[1,0]
	v_max_f32_e32 v172, 0, v172
	v_max_f32_e32 v173, 0, v173
	v_max_f32_e32 v174, 0, v174
	v_max_f32_e32 v175, 0, v175
	v_max_f32_e32 v176, 0, v176
	v_max_f32_e32 v177, 0, v177
	v_max_f32_e32 v178, 0, v178
	v_max_f32_e32 v179, 0, v179
	v_pk_mul_f32 v[172:173], v[172:173], v[172:173]
	v_pk_mul_f32 v[174:175], v[174:175], v[174:175]
	v_pk_mul_f32 v[176:177], v[176:177], v[176:177]
	v_pk_mul_f32 v[178:179], v[178:179], v[178:179]
	v_cvt_pk_bf16_f32 v180, v172, v173
	v_cvt_pk_bf16_f32 v181, v174, v175
	v_cvt_pk_bf16_f32 v182, v176, v177
	v_cvt_pk_bf16_f32 v183, v178, v179
	global_store_dwordx4 v[140:141], v[180:183], off offset:256
	v_lshl_add_u64 v[140:141], v[140:141], 0, s[6:7]
	v_pk_mul_f32 v[144:145], v[94:95], v[240:241] op_sel_hi:[1,0]
	v_pk_mul_f32 v[146:147], v[96:97], v[240:241] op_sel_hi:[1,0]
	v_pk_mul_f32 v[148:149], v[90:91], v[240:241] op_sel_hi:[1,0]
	v_pk_mul_f32 v[150:151], v[92:93], v[240:241] op_sel_hi:[1,0]
	v_max_f32_e32 v144, 0, v144
	v_max_f32_e32 v145, 0, v145
	v_max_f32_e32 v146, 0, v146
	v_max_f32_e32 v147, 0, v147
	v_max_f32_e32 v148, 0, v148
	v_max_f32_e32 v149, 0, v149
	v_max_f32_e32 v150, 0, v150
	v_max_f32_e32 v151, 0, v151
	v_pk_mul_f32 v[144:145], v[144:145], v[144:145]
	v_pk_mul_f32 v[146:147], v[146:147], v[146:147]
	v_pk_mul_f32 v[148:149], v[148:149], v[148:149]
	v_pk_mul_f32 v[150:151], v[150:151], v[150:151]
	v_cvt_pk_bf16_f32 v152, v144, v145
	v_cvt_pk_bf16_f32 v153, v146, v147
	v_cvt_pk_bf16_f32 v154, v148, v149
	v_cvt_pk_bf16_f32 v155, v150, v151
	global_store_dwordx4 v[140:141], v[152:155], off
	v_pk_mul_f32 v[172:173], v[86:87], v[240:241] op_sel_hi:[1,0]
	v_pk_mul_f32 v[174:175], v[88:89], v[240:241] op_sel_hi:[1,0]
	v_pk_mul_f32 v[176:177], v[82:83], v[240:241] op_sel_hi:[1,0]
	v_pk_mul_f32 v[178:179], v[84:85], v[240:241] op_sel_hi:[1,0]
	v_max_f32_e32 v172, 0, v172
	v_max_f32_e32 v173, 0, v173
	v_max_f32_e32 v174, 0, v174
	v_max_f32_e32 v175, 0, v175
	v_max_f32_e32 v176, 0, v176
	v_max_f32_e32 v177, 0, v177
	v_max_f32_e32 v178, 0, v178
	v_max_f32_e32 v179, 0, v179
	v_pk_mul_f32 v[172:173], v[172:173], v[172:173]
	v_pk_mul_f32 v[174:175], v[174:175], v[174:175]
	v_pk_mul_f32 v[176:177], v[176:177], v[176:177]
	v_pk_mul_f32 v[178:179], v[178:179], v[178:179]
	v_cvt_pk_bf16_f32 v180, v172, v173
	v_cvt_pk_bf16_f32 v181, v174, v175
	v_cvt_pk_bf16_f32 v182, v176, v177
	v_cvt_pk_bf16_f32 v183, v178, v179
	global_store_dwordx4 v[140:141], v[180:183], off offset:256
	v_lshl_add_u64 v[140:141], v[140:141], 0, s[6:7]
	v_pk_mul_f32 v[144:145], v[78:79], v[242:243] op_sel_hi:[1,0]
	v_pk_mul_f32 v[146:147], v[80:81], v[242:243] op_sel_hi:[1,0]
	v_pk_mul_f32 v[148:149], v[74:75], v[242:243] op_sel_hi:[1,0]
; #define PG8_GAS __attribute__((address_space(1)))
; __device__ __forceinline__ unsigned cvt_pk_bf16(float lo, float hi) { unsigned r; asm volatile("v_cvt_pk_bf16_f32 %0, %1, %2" : "=v"(r) : "v"(lo), "v"(hi)); return r; }
;     __device__ __forceinline__ void operator()(const f32x4 (&acc)[2][2][4][2], const Unit& u, int wr, int wc, int fr, int fq) const {
;     ...
;                 for (int bj = 0; bj < 2; ++bj) { f32x4 v0 = acc[ai][bj][m][0] * rs, v1 = acc[ai][bj][m][1] * rs;
;                     if (ACT == 1) {
; #pragma unroll
;                         for (int e = 0; e < 4; ++e) { const float a = fmaxf(v0[e], 0.f), b = fmaxf(v1[e], 0.f); v0[e] = a * a; v1[e] = b * b; } }
;                     u32x4 w; w.x = cvt_pk_bf16(v0[0], v0[1]); w.y = cvt_pk_bf16(v0[2], v0[3]); w.z = cvt_pk_bf16(v1[0], v1[1]); w.w = cvt_pk_bf16(v1[2], v1[3]);
;                     *(PG8_GAS u32x4*)(rowp + bj * HALF) = w; } }
	v_pk_mul_f32 v[150:151], v[76:77], v[242:243] op_sel_hi:[1,0]
	v_max_f32_e32 v144, 0, v144
	v_max_f32_e32 v145, 0, v145
	v_max_f32_e32 v146, 0, v146
	v_max_f32_e32 v147, 0, v147
	v_max_f32_e32 v148, 0, v148
	v_max_f32_e32 v149, 0, v149
	v_max_f32_e32 v150, 0, v150
	v_max_f32_e32 v151, 0, v151
	v_pk_mul_f32 v[144:145], v[144:145], v[144:145]
	v_pk_mul_f32 v[146:147], v[146:147], v[146:147]
	v_pk_mul_f32 v[148:149], v[148:149], v[148:149]
	v_pk_mul_f32 v[150:151], v[150:151], v[150:151]
	v_cvt_pk_bf16_f32 v152, v144, v145
	v_cvt_pk_bf16_f32 v153, v146, v147
	v_cvt_pk_bf16_f32 v154, v148, v149
	v_cvt_pk_bf16_f32 v155, v150, v151
	global_store_dwordx4 v[140:141], v[152:155], off
	v_pk_mul_f32 v[172:173], v[70:71], v[242:243] op_sel_hi:[1,0]
	v_pk_mul_f32 v[174:175], v[72:73], v[242:243] op_sel_hi:[1,0]
	v_pk_mul_f32 v[176:177], v[66:67], v[242:243] op_sel_hi:[1,0]
	v_pk_mul_f32 v[178:179], v[68:69], v[242:243] op_sel_hi:[1,0]
	v_max_f32_e32 v172, 0, v172
	v_max_f32_e32 v173, 0, v173
	v_max_f32_e32 v174, 0, v174
	v_max_f32_e32 v175, 0, v175
	v_max_f32_e32 v176, 0, v176
	v_max_f32_e32 v177, 0, v177
	v_max_f32_e32 v178, 0, v178
	v_max_f32_e32 v179, 0, v179
	v_pk_mul_f32 v[172:173], v[172:173], v[172:173]
	v_pk_mul_f32 v[174:175], v[174:175], v[174:175]
	v_pk_mul_f32 v[176:177], v[176:177], v[176:177]
	v_pk_mul_f32 v[178:179], v[178:179], v[178:179]
	v_cvt_pk_bf16_f32 v180, v172, v173
	v_cvt_pk_bf16_f32 v181, v174, v175
	v_cvt_pk_bf16_f32 v182, v176, v177
	v_cvt_pk_bf16_f32 v183, v178, v179
	global_store_dwordx4 v[140:141], v[180:183], off offset:256
	v_lshl_add_u64 v[140:141], v[140:141], 0, s[4:5]
	v_pk_mul_f32 v[144:145], v[62:63], v[244:245] op_sel_hi:[1,0]
	v_pk_mul_f32 v[146:147], v[64:65], v[244:245] op_sel_hi:[1,0]
	v_pk_mul_f32 v[148:149], v[58:59], v[244:245] op_sel_hi:[1,0]
	v_pk_mul_f32 v[150:151], v[60:61], v[244:245] op_sel_hi:[1,0]
	v_max_f32_e32 v144, 0, v144
	v_max_f32_e32 v145, 0, v145
	v_max_f32_e32 v146, 0, v146
	v_max_f32_e32 v147, 0, v147
	v_max_f32_e32 v148, 0, v148
	v_max_f32_e32 v149, 0, v149
	v_max_f32_e32 v150, 0, v150
	v_max_f32_e32 v151, 0, v151
	v_pk_mul_f32 v[144:145], v[144:145], v[144:145]
	v_pk_mul_f32 v[146:147], v[146:147], v[146:147]
	v_pk_mul_f32 v[148:149], v[148:149], v[148:149]
	v_pk_mul_f32 v[150:151], v[150:151], v[150:151]
	v_cvt_pk_bf16_f32 v152, v144, v145
	v_cvt_pk_bf16_f32 v153, v146, v147
	v_cvt_pk_bf16_f32 v154, v148, v149
	v_cvt_pk_bf16_f32 v155, v150, v151
	global_store_dwordx4 v[140:141], v[152:155], off
	v_pk_mul_f32 v[172:173], v[54:55], v[244:245] op_sel_hi:[1,0]
	v_pk_mul_f32 v[174:175], v[56:57], v[244:245] op_sel_hi:[1,0]
	v_pk_mul_f32 v[176:177], v[50:51], v[244:245] op_sel_hi:[1,0]
	v_pk_mul_f32 v[178:179], v[52:53], v[244:245] op_sel_hi:[1,0]
	v_max_f32_e32 v172, 0, v172
	v_max_f32_e32 v173, 0, v173
	v_max_f32_e32 v174, 0, v174
	v_max_f32_e32 v175, 0, v175
	v_max_f32_e32 v176, 0, v176
	v_max_f32_e32 v177, 0, v177
	v_max_f32_e32 v178, 0, v178
	v_max_f32_e32 v179, 0, v179
	v_pk_mul_f32 v[172:173], v[172:173], v[172:173]
	v_pk_mul_f32 v[174:175], v[174:175], v[174:175]
	v_pk_mul_f32 v[176:177], v[176:177], v[176:177]
	v_pk_mul_f32 v[178:179], v[178:179], v[178:179]
	v_cvt_pk_bf16_f32 v180, v172, v173
	v_cvt_pk_bf16_f32 v181, v174, v175
	v_cvt_pk_bf16_f32 v182, v176, v177
	v_cvt_pk_bf16_f32 v183, v178, v179
	global_store_dwordx4 v[140:141], v[180:183], off offset:256
	v_lshl_add_u64 v[140:141], v[140:141], 0, s[6:7]
	v_pk_mul_f32 v[144:145], v[46:47], v[246:247] op_sel_hi:[1,0]
	v_pk_mul_f32 v[146:147], v[48:49], v[246:247] op_sel_hi:[1,0]
	v_pk_mul_f32 v[148:149], v[42:43], v[246:247] op_sel_hi:[1,0]
	v_pk_mul_f32 v[150:151], v[44:45], v[246:247] op_sel_hi:[1,0]
	v_max_f32_e32 v144, 0, v144
	v_max_f32_e32 v145, 0, v145
	v_max_f32_e32 v146, 0, v146
	v_max_f32_e32 v147, 0, v147
	v_max_f32_e32 v148, 0, v148
	v_max_f32_e32 v149, 0, v149
	v_max_f32_e32 v150, 0, v150
	v_max_f32_e32 v151, 0, v151
	v_pk_mul_f32 v[144:145], v[144:145], v[144:145]
	v_pk_mul_f32 v[146:147], v[146:147], v[146:147]
	v_pk_mul_f32 v[148:149], v[148:149], v[148:149]
	v_pk_mul_f32 v[150:151], v[150:151], v[150:151]
	v_cvt_pk_bf16_f32 v152, v144, v145
	v_cvt_pk_bf16_f32 v153, v146, v147
	v_cvt_pk_bf16_f32 v154, v148, v149
	v_cvt_pk_bf16_f32 v155, v150, v151
	global_store_dwordx4 v[140:141], v[152:155], off
	v_pk_mul_f32 v[172:173], v[38:39], v[246:247] op_sel_hi:[1,0]
	v_pk_mul_f32 v[174:175], v[40:41], v[246:247] op_sel_hi:[1,0]
	v_pk_mul_f32 v[176:177], v[34:35], v[246:247] op_sel_hi:[1,0]
; #define PG8_GAS __attribute__((address_space(1)))
; __device__ __forceinline__ unsigned cvt_pk_bf16(float lo, float hi) { unsigned r; asm volatile("v_cvt_pk_bf16_f32 %0, %1, %2" : "=v"(r) : "v"(lo), "v"(hi)); return r; }
; #define PG8_BAR __builtin_amdgcn_s_barrier()
;     __device__ __forceinline__ void operator()(const f32x4 (&acc)[2][2][4][2], const Unit& u, int wr, int wc, int fr, int fq) const {
;     ...
;                 for (int bj = 0; bj < 2; ++bj) { f32x4 v0 = acc[ai][bj][m][0] * rs, v1 = acc[ai][bj][m][1] * rs;
;                     if (ACT == 1) {
; #pragma unroll
;                         for (int e = 0; e < 4; ++e) { const float a = fmaxf(v0[e], 0.f), b = fmaxf(v1[e], 0.f); v0[e] = a * a; v1[e] = b * b; } }
;                     u32x4 w; w.x = cvt_pk_bf16(v0[0], v0[1]); w.y = cvt_pk_bf16(v0[2], v0[3]); w.z = cvt_pk_bf16(v1[0], v1[1]); w.w = cvt_pk_bf16(v1[2], v1[3]);
;                     *(PG8_GAS u32x4*)(rowp + bj * HALF) = w; } }
; template <class Epi, class Sched, bool ALIGN_EPI = false, bool SP2 = false>
; __device__ __forceinline__ void gemm_phase(PG8_LAS unsigned char* lds, const Gemm g, const Sched& S, const Epi& E) {
;     ...
;         if constexpr (ALIGN_EPI) { if (wr == 0) PG8_BAR; }
;         if constexpr (!Epi::AFTER_DRAIN) { E(acc, cur, wr, wc, fr, fq); S.done(cur); }
;         if (!has_next) break;
	v_pk_mul_f32 v[178:179], v[36:37], v[246:247] op_sel_hi:[1,0]
	v_max_f32_e32 v172, 0, v172
	v_max_f32_e32 v173, 0, v173
	v_max_f32_e32 v174, 0, v174
	v_max_f32_e32 v175, 0, v175
	v_max_f32_e32 v176, 0, v176
	v_max_f32_e32 v177, 0, v177
	v_max_f32_e32 v178, 0, v178
	v_max_f32_e32 v179, 0, v179
	v_pk_mul_f32 v[172:173], v[172:173], v[172:173]
	v_pk_mul_f32 v[174:175], v[174:175], v[174:175]
	v_pk_mul_f32 v[176:177], v[176:177], v[176:177]
	v_pk_mul_f32 v[178:179], v[178:179], v[178:179]
	v_cvt_pk_bf16_f32 v180, v172, v173
	v_cvt_pk_bf16_f32 v181, v174, v175
	v_cvt_pk_bf16_f32 v182, v176, v177
	v_cvt_pk_bf16_f32 v183, v178, v179
	global_store_dwordx4 v[140:141], v[180:183], off offset:256
	v_lshl_add_u64 v[140:141], v[140:141], 0, s[6:7]
	v_pk_mul_f32 v[144:145], v[30:31], v[248:249] op_sel_hi:[1,0]
	v_pk_mul_f32 v[146:147], v[32:33], v[248:249] op_sel_hi:[1,0]
	v_pk_mul_f32 v[148:149], v[26:27], v[248:249] op_sel_hi:[1,0]
	v_pk_mul_f32 v[150:151], v[28:29], v[248:249] op_sel_hi:[1,0]
	v_max_f32_e32 v144, 0, v144
	v_max_f32_e32 v145, 0, v145
	v_max_f32_e32 v146, 0, v146
	v_max_f32_e32 v147, 0, v147
	v_max_f32_e32 v148, 0, v148
	v_max_f32_e32 v149, 0, v149
	v_max_f32_e32 v150, 0, v150
	v_max_f32_e32 v151, 0, v151
	v_pk_mul_f32 v[144:145], v[144:145], v[144:145]
	v_pk_mul_f32 v[146:147], v[146:147], v[146:147]
	v_pk_mul_f32 v[148:149], v[148:149], v[148:149]
	v_pk_mul_f32 v[150:151], v[150:151], v[150:151]
	v_cvt_pk_bf16_f32 v152, v144, v145
	v_cvt_pk_bf16_f32 v153, v146, v147
	v_cvt_pk_bf16_f32 v154, v148, v149
	v_cvt_pk_bf16_f32 v155, v150, v151
	global_store_dwordx4 v[140:141], v[152:155], off
	v_pk_mul_f32 v[172:173], v[22:23], v[248:249] op_sel_hi:[1,0]
	v_pk_mul_f32 v[174:175], v[24:25], v[248:249] op_sel_hi:[1,0]
	v_pk_mul_f32 v[176:177], v[18:19], v[248:249] op_sel_hi:[1,0]
	v_pk_mul_f32 v[178:179], v[20:21], v[248:249] op_sel_hi:[1,0]
	v_max_f32_e32 v172, 0, v172
	v_max_f32_e32 v173, 0, v173
	v_max_f32_e32 v174, 0, v174
	v_max_f32_e32 v175, 0, v175
	v_max_f32_e32 v176, 0, v176
	v_max_f32_e32 v177, 0, v177
	v_max_f32_e32 v178, 0, v178
	v_max_f32_e32 v179, 0, v179
	v_pk_mul_f32 v[172:173], v[172:173], v[172:173]
	v_pk_mul_f32 v[174:175], v[174:175], v[174:175]
	v_pk_mul_f32 v[176:177], v[176:177], v[176:177]
	v_pk_mul_f32 v[178:179], v[178:179], v[178:179]
	v_cvt_pk_bf16_f32 v180, v172, v173
	v_cvt_pk_bf16_f32 v181, v174, v175
	v_cvt_pk_bf16_f32 v182, v176, v177
	v_cvt_pk_bf16_f32 v183, v178, v179
	global_store_dwordx4 v[140:141], v[180:183], off offset:256
	v_lshl_add_u64 v[140:141], v[140:141], 0, s[6:7]
	v_pk_mul_f32 v[144:145], v[14:15], v[252:253] op_sel_hi:[1,0]
	v_pk_mul_f32 v[146:147], v[16:17], v[252:253] op_sel_hi:[1,0]
	v_pk_mul_f32 v[148:149], v[10:11], v[252:253] op_sel_hi:[1,0]
	v_pk_mul_f32 v[150:151], v[12:13], v[252:253] op_sel_hi:[1,0]
	v_max_f32_e32 v144, 0, v144
	v_max_f32_e32 v145, 0, v145
	v_max_f32_e32 v146, 0, v146
	v_max_f32_e32 v147, 0, v147
	v_max_f32_e32 v148, 0, v148
	v_max_f32_e32 v149, 0, v149
	v_max_f32_e32 v150, 0, v150
	v_max_f32_e32 v151, 0, v151
	v_pk_mul_f32 v[144:145], v[144:145], v[144:145]
	v_pk_mul_f32 v[146:147], v[146:147], v[146:147]
	v_pk_mul_f32 v[148:149], v[148:149], v[148:149]
	v_pk_mul_f32 v[150:151], v[150:151], v[150:151]
	v_cvt_pk_bf16_f32 v152, v144, v145
	v_cvt_pk_bf16_f32 v153, v146, v147
	v_cvt_pk_bf16_f32 v154, v148, v149
	v_cvt_pk_bf16_f32 v155, v150, v151
	global_store_dwordx4 v[140:141], v[152:155], off
	v_pk_mul_f32 v[172:173], v[6:7], v[252:253] op_sel_hi:[1,0]
	v_pk_mul_f32 v[174:175], v[8:9], v[252:253] op_sel_hi:[1,0]
	v_pk_mul_f32 v[176:177], v[2:3], v[252:253] op_sel_hi:[1,0]
	v_pk_mul_f32 v[178:179], v[4:5], v[252:253] op_sel_hi:[1,0]
	v_max_f32_e32 v172, 0, v172
	v_max_f32_e32 v173, 0, v173
	v_max_f32_e32 v174, 0, v174
	v_max_f32_e32 v175, 0, v175
	v_max_f32_e32 v176, 0, v176
	v_max_f32_e32 v177, 0, v177
	v_max_f32_e32 v178, 0, v178
	v_max_f32_e32 v179, 0, v179
	v_pk_mul_f32 v[172:173], v[172:173], v[172:173]
	v_pk_mul_f32 v[174:175], v[174:175], v[174:175]
	v_pk_mul_f32 v[176:177], v[176:177], v[176:177]
	v_pk_mul_f32 v[178:179], v[178:179], v[178:179]
	v_cvt_pk_bf16_f32 v180, v172, v173
	v_cvt_pk_bf16_f32 v181, v174, v175
	v_cvt_pk_bf16_f32 v182, v176, v177
	v_cvt_pk_bf16_f32 v183, v178, v179
	global_store_dwordx4 v[140:141], v[180:183], off offset:256
.Lmy_epi_done:
	s_and_b64 vcc, exec, s[40:41]
	s_mov_b64 s[4:5], -1
	s_cbranch_vccnz .LBB0_219
.LBB0_255:
	s_andn2_b64 vcc, exec, s[54:55]
	s_cbranch_vccnz .LBB0_218
	s_barrier
	s_branch .LBB0_218
